# GU unit loop: accumulator zeroing moved into a peeled copy of the first load segment (hidden under the fragment LDS reads)
# baseline (speedup 1.0000x reference)
; #define PG8_STAGE(bufoff, gbase, voff) do { _Pragma("unroll") for (int _i = 0; _i < 2; ++_i) \
;         __builtin_amdgcn_global_load_lds((const unsigned*)((const char*)(gbase) + (voff)[_i]), (PG8_LAS unsigned*)(lds + (bufoff) + ldsw + _i * 8192), 16, 0, 0); } while (0)
; #define PG8_LDA(dst, b, h) do { _Pragma("unroll") for (int m = 0; m < 4; ++m) _Pragma("unroll") for (int k = 0; k < 2; ++k) dst[m][k] = *(const PG8_LAS bf16x8*)(lds + PG8_SA(b, h) + aoff + m * 2048 + k * 1024); } while (0)
; #define PG8_LDB(dst, b, h) do { _Pragma("unroll") for (int n = 0; n < 2; ++n) _Pragma("unroll") for (int k = 0; k < 2; ++k) dst[n][k] = *(const PG8_LAS bf16x8*)(lds + PG8_SB(b, h) + boff + n * 2048 + k * 1024); } while (0)
; #define PG8_MMA(ai, bj, At, Bt) do { __builtin_amdgcn_s_setprio(1); _Pragma("unroll") for (int m = 0; m < 4; ++m) _Pragma("unroll") for (int n = 0; n < 2; ++n) _Pragma("unroll") for (int k = 0; k < 2; ++k) \
;         acc[ai][bj][m][n] = __builtin_amdgcn_mfma_f32_16x16x32_bf16(Bt[n][k], At[m][k], acc[ai][bj][m][n], 0, 0, 0); __builtin_amdgcn_s_setprio(0); } while (0)
; #define PG8_WAIT_V(n) asm volatile("s_waitcnt vmcnt(" #n ")" ::: "memory")
; #define PG8_WAIT_L(n) asm volatile("s_waitcnt lgkmcnt(" #n ")" ::: "memory")
; #define PG8_BAR __builtin_amdgcn_s_barrier()
; #define PG8_SCHED __builtin_amdgcn_sched_barrier(0)
; template <class Epi, class Sched, bool ALIGN_EPI = false, bool SP2 = false, bool HALFM = false>
; __device__ __forceinline__ void gemm_phase(PG8_LAS unsigned char* lds, const Gemm g, const Sched& S, const Epi& E) {
;     ...
;             PG8_LDB(B0, 0, 0); PG8_LDB(B1, 0, 1); PG8_SCHED; PG8_LDA(At, 0, 0); PG8_STAGE(PG8_SA(1, 1), a1 + hstep, voffA);
;             PG8_WAIT_V(8); PG8_WAIT_L(0); PG8_BAR; PG8_MMA(0, 0, At, B0); PG8_MMA(0, 1, At, B1); PG8_BAR; PG8_SCHED;
;     ...
; #pragma unroll
;         for (int a = 0; a < 2; ++a)
; #pragma unroll
;             for (int b = 0; b < 2; ++b)
; #pragma unroll
;                 for (int m = 0; m < 4; ++m)
; #pragma unroll
;                     for (int n = 0; n < 2; ++n) acc[a][b][m][n] = (f32x4){0.f, 0.f, 0.f, 0.f};
;         cur = nxt; cA = nA; cB = nB; ++ui;
.LBB0_177:
	s_ashr_i32 s11, s10, 31
	s_xor_b64 s[16:17], s[18:19], -1
	s_lshl_b64 s[12:13], s[10:11], 19
	s_add_u32 s12, s30, s12
	s_addc_u32 s13, s31, s13
	s_and_b64 s[14:15], exec, s[18:19]
	s_cselect_b32 s11, s23, s13
	s_cselect_b32 s58, s22, s12
	s_ashr_i32 s9, s8, 31
	s_lshl_b64 s[14:15], s[8:9], 19
	s_add_u32 s14, s29, s14
	s_addc_u32 s15, s45, s15
	s_and_b64 s[20:21], exec, s[18:19]
	s_cselect_b32 s9, s25, s15
	s_cselect_b32 s59, s24, s14
	s_lshl_b32 s60, s10, 8
	s_lshl_b32 s26, s54, 10
	s_cmp_eq_u32 s10, s28
	s_cselect_b64 s[20:21], -1, 0
	s_add_i32 s61, s26, 0
	s_add_i32 s61, s61, 0x24900
	s_add_u32 s22, s22, 0x40080
	s_addc_u32 s23, s23, 0
	s_add_u32 s62, s24, 0x100
	s_addc_u32 s63, s25, 0
	s_mov_b32 s64, -2
	s_branch .Lgu_first
.Lgu_first:
	s_mov_b64 s[24:25], -1
	s_add_u32 s26, s22, 0xfffc0080
	s_addc_u32 s27, s23, -1
	s_and_b64 s[24:25], s[24:25], exec
	s_cselect_b32 s27, s27, s11
	s_cselect_b32 s26, s26, s58
	s_cselect_b32 s25, s63, s9
	s_cselect_b32 s24, s62, s59
	s_add_i32 s65, 0, 0x10000
	v_add_u32_e32 v140, s65, v143
	s_add_i32 s68, 0, 0x14000
	ds_read_b128 v[148:151], v140
	ds_read_b128 v[160:163], v140 offset:1024
	ds_read_b128 v[164:167], v140 offset:2048
	ds_read_b128 v[168:171], v140 offset:3072
	v_add_u32_e32 v140, s68, v143
	ds_read_b128 v[172:175], v140
	ds_read_b128 v[176:179], v140 offset:1024
	ds_read_b128 v[180:183], v140 offset:2048
	ds_read_b128 v[184:187], v140 offset:3072
	v_lshl_add_u64 v[140:141], s[22:23], 0, v[136:137]
	s_add_i32 m0, s47, 0xc000
	ds_read_b128 v[202:205], v146
	ds_read_b128 v[206:209], v146 offset:1024
	ds_read_b128 v[210:213], v146 offset:2048
	ds_read_b128 v[214:217], v146 offset:3072
	ds_read_b128 v[218:221], v146 offset:4096
	ds_read_b128 v[222:225], v146 offset:5120
	ds_read_b128 v[226:229], v146 offset:6144
	ds_read_b128 v[230:233], v146 offset:7168
	v_mov_b32_e32 v0, 0
	v_mov_b32_e32 v1, 0
	v_mov_b64_e32 v[2:3], 0
	v_mov_b64_e32 v[4:5], 0
	v_mov_b64_e32 v[6:7], 0
	v_mov_b64_e32 v[8:9], 0
	v_mov_b64_e32 v[10:11], 0
	v_mov_b64_e32 v[12:13], 0
	v_mov_b64_e32 v[14:15], 0
	v_mov_b64_e32 v[16:17], 0
	v_mov_b64_e32 v[18:19], 0
	v_mov_b64_e32 v[20:21], 0
	v_mov_b64_e32 v[22:23], 0
	v_mov_b64_e32 v[24:25], 0
	v_mov_b64_e32 v[26:27], 0
	v_mov_b64_e32 v[28:29], 0
	v_mov_b64_e32 v[30:31], 0
	v_mov_b64_e32 v[32:33], 0
	v_mov_b64_e32 v[34:35], 0
	v_mov_b64_e32 v[36:37], 0
	v_mov_b64_e32 v[38:39], 0
	v_mov_b64_e32 v[40:41], 0
	v_mov_b64_e32 v[42:43], 0
	v_mov_b64_e32 v[44:45], 0
	v_mov_b64_e32 v[46:47], 0
	v_mov_b64_e32 v[48:49], 0
	v_mov_b64_e32 v[50:51], 0
	v_mov_b64_e32 v[52:53], 0
	v_mov_b64_e32 v[54:55], 0
	v_mov_b64_e32 v[56:57], 0
	v_mov_b64_e32 v[58:59], 0
	v_mov_b64_e32 v[60:61], 0
	v_mov_b64_e32 v[62:63], 0
	v_mov_b64_e32 v[64:65], 0
	v_mov_b64_e32 v[66:67], 0
	v_mov_b64_e32 v[68:69], 0
	v_mov_b64_e32 v[70:71], 0
	v_mov_b64_e32 v[72:73], 0
	v_mov_b64_e32 v[74:75], 0
	v_mov_b64_e32 v[76:77], 0
	v_mov_b64_e32 v[78:79], 0
	v_mov_b64_e32 v[82:83], 0
	v_mov_b64_e32 v[84:85], 0
	v_mov_b64_e32 v[86:87], 0
	v_mov_b64_e32 v[88:89], 0
	v_mov_b64_e32 v[90:91], 0
	v_mov_b64_e32 v[92:93], 0
	v_mov_b64_e32 v[94:95], 0
	v_mov_b64_e32 v[96:97], 0
	v_mov_b64_e32 v[98:99], 0
	v_mov_b64_e32 v[100:101], 0
	v_mov_b64_e32 v[102:103], 0
	v_mov_b64_e32 v[104:105], 0
	v_mov_b64_e32 v[106:107], 0
	v_mov_b64_e32 v[108:109], 0
	v_mov_b64_e32 v[110:111], 0
	v_mov_b64_e32 v[112:113], 0
	v_mov_b64_e32 v[114:115], 0
	v_mov_b64_e32 v[116:117], 0
	v_mov_b64_e32 v[118:119], 0
	v_mov_b64_e32 v[120:121], 0
	v_mov_b64_e32 v[122:123], 0
	v_mov_b64_e32 v[124:125], 0
	v_mov_b64_e32 v[126:127], 0
	v_mov_b64_e32 v[128:129], 0
	global_load_lds_dwordx4 v[140:141], off
	v_lshl_add_u64 v[140:141], s[22:23], 0, v[138:139]
	s_add_i32 m0, s47, 0xe000
	s_nop 0
	global_load_lds_dwordx4 v[140:141], off
	s_branch .Lgu_body_wait

; #define PG8_STAGE(bufoff, gbase, voff) do { _Pragma("unroll") for (int _i = 0; _i < 2; ++_i) \
;         __builtin_amdgcn_global_load_lds((const unsigned*)((const char*)(gbase) + (voff)[_i]), (PG8_LAS unsigned*)(lds + (bufoff) + ldsw + _i * 8192), 16, 0, 0); } while (0)
; #define PG8_LDA(dst, b, h) do { _Pragma("unroll") for (int m = 0; m < 4; ++m) _Pragma("unroll") for (int k = 0; k < 2; ++k) dst[m][k] = *(const PG8_LAS bf16x8*)(lds + PG8_SA(b, h) + aoff + m * 2048 + k * 1024); } while (0)
; #define PG8_MMA(ai, bj, At, Bt) do { __builtin_amdgcn_s_setprio(1); _Pragma("unroll") for (int m = 0; m < 4; ++m) _Pragma("unroll") for (int n = 0; n < 2; ++n) _Pragma("unroll") for (int k = 0; k < 2; ++k) \
;         acc[ai][bj][m][n] = __builtin_amdgcn_mfma_f32_16x16x32_bf16(Bt[n][k], At[m][k], acc[ai][bj][m][n], 0, 0, 0); __builtin_amdgcn_s_setprio(0); } while (0)
; #define PG8_WAIT_V(n) asm volatile("s_waitcnt vmcnt(" #n ")" ::: "memory")
; #define PG8_WAIT_L(n) asm volatile("s_waitcnt lgkmcnt(" #n ")" ::: "memory")
; #define PG8_BAR __builtin_amdgcn_s_barrier()
; #define PG8_SCHED __builtin_amdgcn_sched_barrier(0)
; template <class Epi, class Sched, bool ALIGN_EPI = false, bool SP2 = false, bool HALFM = false>
; __device__ __forceinline__ void gemm_phase(PG8_LAS unsigned char* lds, const Gemm g, const Sched& S, const Epi& E) {
;     ...
;             PG8_WAIT_V(8); PG8_WAIT_L(0); PG8_BAR; PG8_MMA(0, 0, At, B0); PG8_MMA(0, 1, At, B1); PG8_BAR; PG8_SCHED;
;             if constexpr (!HALFM) PG8_LDA(At, 0, 1); PG8_STAGE(PG8_SB(0, 0), b2, voffB); PG8_STAGE(PG8_SB(0, 1), b2 + hstep, voffB); PG8_STAGE(PG8_SA(0, 0), a2, voffA);
;             PG8_WAIT_V(8); PG8_WAIT_L(0); PG8_BAR; if constexpr (!HALFM) { PG8_MMA(1, 0, At, B0); PG8_MMA(1, 1, At, B1); } PG8_BAR; PG8_SCHED;
.Lgu_body_wait:
	s_waitcnt vmcnt(8)
	s_waitcnt lgkmcnt(0)
	s_setprio 1
	s_barrier
	v_mfma_f32_16x16x32_bf16 v[126:129], v[148:151], v[202:205], v[126:129]
	v_mfma_f32_16x16x32_bf16 v[122:125], v[164:167], v[202:205], v[122:125]
	v_mfma_f32_16x16x32_bf16 v[110:113], v[148:151], v[210:213], v[110:113]
	v_mfma_f32_16x16x32_bf16 v[106:109], v[164:167], v[210:213], v[106:109]
	v_mfma_f32_16x16x32_bf16 v[94:97], v[148:151], v[218:221], v[94:97]
	v_mfma_f32_16x16x32_bf16 v[90:93], v[164:167], v[218:221], v[90:93]
	v_mfma_f32_16x16x32_bf16 v[76:79], v[148:151], v[226:229], v[76:79]
	v_mfma_f32_16x16x32_bf16 v[72:75], v[164:167], v[226:229], v[72:75]
	v_mfma_f32_16x16x32_bf16 v[126:129], v[160:163], v[206:209], v[126:129]
	v_mfma_f32_16x16x32_bf16 v[122:125], v[168:171], v[206:209], v[122:125]
	v_mfma_f32_16x16x32_bf16 v[110:113], v[160:163], v[214:217], v[110:113]
	v_mfma_f32_16x16x32_bf16 v[106:109], v[168:171], v[214:217], v[106:109]
	v_mfma_f32_16x16x32_bf16 v[94:97], v[160:163], v[222:225], v[94:97]
	v_mfma_f32_16x16x32_bf16 v[90:93], v[168:171], v[222:225], v[90:93]
	v_mfma_f32_16x16x32_bf16 v[76:79], v[160:163], v[230:233], v[76:79]
	v_mfma_f32_16x16x32_bf16 v[72:75], v[168:171], v[230:233], v[72:75]
	v_mfma_f32_16x16x32_bf16 v[118:121], v[172:175], v[202:205], v[118:121]
	v_mfma_f32_16x16x32_bf16 v[114:117], v[180:183], v[202:205], v[114:117]
	v_mfma_f32_16x16x32_bf16 v[102:105], v[172:175], v[210:213], v[102:105]
	v_mfma_f32_16x16x32_bf16 v[98:101], v[180:183], v[210:213], v[98:101]
	v_mfma_f32_16x16x32_bf16 v[86:89], v[172:175], v[218:221], v[86:89]
	v_mfma_f32_16x16x32_bf16 v[82:85], v[180:183], v[218:221], v[82:85]
	v_mfma_f32_16x16x32_bf16 v[68:71], v[172:175], v[226:229], v[68:71]
	v_mfma_f32_16x16x32_bf16 v[64:67], v[180:183], v[226:229], v[64:67]
	v_mfma_f32_16x16x32_bf16 v[118:121], v[176:179], v[206:209], v[118:121]
	v_mfma_f32_16x16x32_bf16 v[114:117], v[184:187], v[206:209], v[114:117]
	v_mfma_f32_16x16x32_bf16 v[102:105], v[176:179], v[214:217], v[102:105]
	v_mfma_f32_16x16x32_bf16 v[98:101], v[184:187], v[214:217], v[98:101]
	v_mfma_f32_16x16x32_bf16 v[86:89], v[176:179], v[222:225], v[86:89]
	v_mfma_f32_16x16x32_bf16 v[82:85], v[184:187], v[222:225], v[82:85]
	v_mfma_f32_16x16x32_bf16 v[68:71], v[176:179], v[230:233], v[68:71]
	v_mfma_f32_16x16x32_bf16 v[64:67], v[184:187], v[230:233], v[64:67]
	s_barrier
	s_setprio 0
	s_add_i32 s65, s65, s46
	v_lshl_add_u64 v[140:141], s[24:25], 0, v[80:81]
	s_mov_b32 m0, s65
	ds_read_b128 v[202:205], v146 offset:16384
	ds_read_b128 v[206:209], v146 offset:17408
	ds_read_b128 v[210:213], v146 offset:18432
	ds_read_b128 v[214:217], v146 offset:19456
	ds_read_b128 v[218:221], v146 offset:20480
	ds_read_b128 v[222:225], v146 offset:21504
	ds_read_b128 v[226:229], v146 offset:22528
	ds_read_b128 v[230:233], v146 offset:23552
	global_load_lds_dwordx4 v[140:141], off
	s_add_i32 m0, s65, 0x2000
	s_add_u32 s66, s24, 0x40000
	v_lshl_add_u64 v[152:153], s[24:25], 0, v[134:135]
	s_addc_u32 s67, s25, 0
	s_add_i32 s65, s68, s46
	global_load_lds_dwordx4 v[152:153], off
	v_lshl_add_u64 v[188:189], s[66:67], 0, v[80:81]
	s_mov_b32 m0, s65
	v_lshl_add_u64 v[196:197], s[26:27], 0, v[132:133]
	global_load_lds_dwordx4 v[188:189], off
	v_lshl_add_u64 v[188:189], s[66:67], 0, v[134:135]
	s_add_i32 m0, s65, 0x2000
	s_nop 0
	global_load_lds_dwordx4 v[188:189], off
	v_lshl_add_u64 v[188:189], s[26:27], 0, v[130:131]
	s_mov_b32 m0, s47
	s_nop 0
	global_load_lds_dwordx4 v[188:189], off
	s_mov_b32 m0, s48
	s_nop 0
	global_load_lds_dwordx4 v[196:197], off
	s_waitcnt vmcnt(8)
	s_waitcnt lgkmcnt(0)
	s_setprio 1
	s_barrier
	v_mfma_f32_16x16x32_bf16 v[60:63], v[148:151], v[202:205], v[60:63]
	v_mfma_f32_16x16x32_bf16 v[56:59], v[164:167], v[202:205], v[56:59]
	v_mfma_f32_16x16x32_bf16 v[44:47], v[148:151], v[210:213], v[44:47]
	v_mfma_f32_16x16x32_bf16 v[40:43], v[164:167], v[210:213], v[40:43]
	v_mfma_f32_16x16x32_bf16 v[28:31], v[148:151], v[218:221], v[28:31]
	v_mfma_f32_16x16x32_bf16 v[24:27], v[164:167], v[218:221], v[24:27]
	v_mfma_f32_16x16x32_bf16 v[12:15], v[148:151], v[226:229], v[12:15]
	v_mfma_f32_16x16x32_bf16 v[8:11], v[164:167], v[226:229], v[8:11]
	v_mfma_f32_16x16x32_bf16 v[60:63], v[160:163], v[206:209], v[60:63]
	v_mfma_f32_16x16x32_bf16 v[56:59], v[168:171], v[206:209], v[56:59]
	v_mfma_f32_16x16x32_bf16 v[44:47], v[160:163], v[214:217], v[44:47]
	v_mfma_f32_16x16x32_bf16 v[40:43], v[168:171], v[214:217], v[40:43]
	v_mfma_f32_16x16x32_bf16 v[28:31], v[160:163], v[222:225], v[28:31]
	v_mfma_f32_16x16x32_bf16 v[24:27], v[168:171], v[222:225], v[24:27]
	v_mfma_f32_16x16x32_bf16 v[12:15], v[160:163], v[230:233], v[12:15]
	v_mfma_f32_16x16x32_bf16 v[8:11], v[168:171], v[230:233], v[8:11]
	v_mfma_f32_16x16x32_bf16 v[52:55], v[172:175], v[202:205], v[52:55]
	v_mfma_f32_16x16x32_bf16 v[48:51], v[180:183], v[202:205], v[48:51]
	v_mfma_f32_16x16x32_bf16 v[36:39], v[172:175], v[210:213], v[36:39]
	v_mfma_f32_16x16x32_bf16 v[32:35], v[180:183], v[210:213], v[32:35]
	v_mfma_f32_16x16x32_bf16 v[20:23], v[172:175], v[218:221], v[20:23]
	v_mfma_f32_16x16x32_bf16 v[16:19], v[180:183], v[218:221], v[16:19]
	v_mfma_f32_16x16x32_bf16 v[4:7], v[172:175], v[226:229], v[4:7]
	v_mfma_f32_16x16x32_bf16 v[0:3], v[180:183], v[226:229], v[0:3]
	v_mfma_f32_16x16x32_bf16 v[52:55], v[176:179], v[206:209], v[52:55]
	v_mfma_f32_16x16x32_bf16 v[48:51], v[184:187], v[206:209], v[48:51]
	v_mfma_f32_16x16x32_bf16 v[36:39], v[176:179], v[214:217], v[36:39]
	v_mfma_f32_16x16x32_bf16 v[32:35], v[184:187], v[214:217], v[32:35]
	v_mfma_f32_16x16x32_bf16 v[20:23], v[176:179], v[222:225], v[20:23]
	v_mfma_f32_16x16x32_bf16 v[16:19], v[184:187], v[222:225], v[16:19]
	v_mfma_f32_16x16x32_bf16 v[4:7], v[176:179], v[230:233], v[4:7]
	v_mfma_f32_16x16x32_bf16 v[0:3], v[184:187], v[230:233], v[0:3]
	s_barrier
; #define PG8_STAGE(bufoff, gbase, voff) do { _Pragma("unroll") for (int _i = 0; _i < 2; ++_i) \
;         __builtin_amdgcn_global_load_lds((const unsigned*)((const char*)(gbase) + (voff)[_i]), (PG8_LAS unsigned*)(lds + (bufoff) + ldsw + _i * 8192), 16, 0, 0); } while (0)
; #define PG8_LDA(dst, b, h) do { _Pragma("unroll") for (int m = 0; m < 4; ++m) _Pragma("unroll") for (int k = 0; k < 2; ++k) dst[m][k] = *(const PG8_LAS bf16x8*)(lds + PG8_SA(b, h) + aoff + m * 2048 + k * 1024); } while (0)
; #define PG8_LDB(dst, b, h) do { _Pragma("unroll") for (int n = 0; n < 2; ++n) _Pragma("unroll") for (int k = 0; k < 2; ++k) dst[n][k] = *(const PG8_LAS bf16x8*)(lds + PG8_SB(b, h) + boff + n * 2048 + k * 1024); } while (0)
; #define PG8_MMA(ai, bj, At, Bt) do { __builtin_amdgcn_s_setprio(1); _Pragma("unroll") for (int m = 0; m < 4; ++m) _Pragma("unroll") for (int n = 0; n < 2; ++n) _Pragma("unroll") for (int k = 0; k < 2; ++k) \
;         acc[ai][bj][m][n] = __builtin_amdgcn_mfma_f32_16x16x32_bf16(Bt[n][k], At[m][k], acc[ai][bj][m][n], 0, 0, 0); __builtin_amdgcn_s_setprio(0); } while (0)
; #define PG8_WAIT_V(n) asm volatile("s_waitcnt vmcnt(" #n ")" ::: "memory")
; #define PG8_WAIT_L(n) asm volatile("s_waitcnt lgkmcnt(" #n ")" ::: "memory")
; #define PG8_BAR __builtin_amdgcn_s_barrier()
; #define PG8_SCHED __builtin_amdgcn_sched_barrier(0)
; template <class Epi, class Sched, bool ALIGN_EPI = false, bool SP2 = false, bool HALFM = false>
; __device__ __forceinline__ void gemm_phase(PG8_LAS unsigned char* lds, const Gemm g, const Sched& S, const Epi& E) {
;     ...
;             PG8_LDB(B0, 1, 0); PG8_LDB(B1, 1, 1); PG8_SCHED; PG8_LDA(At, 1, 0); PG8_STAGE(PG8_SA(0, 1), a2 + hstep, voffA);
;             PG8_WAIT_V(8); PG8_WAIT_L(0); PG8_BAR; PG8_MMA(0, 0, At, B0); PG8_MMA(0, 1, At, B1); PG8_BAR; PG8_SCHED;
	s_setprio 0
	s_add_i32 s65, 0, 0x18000
	v_add_u32_e32 v147, s65, v143
	s_add_i32 s66, 0, 0x1c000
	ds_read_b128 v[148:151], v147
	ds_read_b128 v[160:163], v147 offset:1024
	ds_read_b128 v[164:167], v147 offset:2048
	ds_read_b128 v[168:171], v147 offset:3072
	v_add_u32_e32 v147, s66, v143
	ds_read_b128 v[172:175], v147
	ds_read_b128 v[176:179], v147 offset:1024
	ds_read_b128 v[180:183], v147 offset:2048
	ds_read_b128 v[184:187], v147 offset:3072
	s_add_u32 s26, s26, 0x40000
	s_addc_u32 s27, s27, 0
	s_mov_b32 m0, s49
	v_lshl_add_u64 v[198:199], s[26:27], 0, v[130:131]
	ds_read_b128 v[202:205], v146 offset:32768
	ds_read_b128 v[206:209], v146 offset:33792
	ds_read_b128 v[210:213], v146 offset:34816
	ds_read_b128 v[214:217], v146 offset:35840
	ds_read_b128 v[218:221], v146 offset:36864
	ds_read_b128 v[222:225], v146 offset:37888
	ds_read_b128 v[226:229], v146 offset:38912
	ds_read_b128 v[230:233], v146 offset:39936
	global_load_lds_dwordx4 v[198:199], off
	v_lshl_add_u64 v[198:199], s[26:27], 0, v[132:133]
	s_mov_b32 m0, s50
	s_nop 0
	global_load_lds_dwordx4 v[198:199], off
	s_waitcnt vmcnt(8)
	s_waitcnt lgkmcnt(0)
	s_setprio 1
	s_barrier
	v_mfma_f32_16x16x32_bf16 v[126:129], v[148:151], v[202:205], v[126:129]
	v_mfma_f32_16x16x32_bf16 v[122:125], v[164:167], v[202:205], v[122:125]
	v_mfma_f32_16x16x32_bf16 v[110:113], v[148:151], v[210:213], v[110:113]
	v_mfma_f32_16x16x32_bf16 v[106:109], v[164:167], v[210:213], v[106:109]
	v_mfma_f32_16x16x32_bf16 v[94:97], v[148:151], v[218:221], v[94:97]
	v_mfma_f32_16x16x32_bf16 v[90:93], v[164:167], v[218:221], v[90:93]
	v_mfma_f32_16x16x32_bf16 v[76:79], v[148:151], v[226:229], v[76:79]
	v_mfma_f32_16x16x32_bf16 v[72:75], v[164:167], v[226:229], v[72:75]
	v_mfma_f32_16x16x32_bf16 v[126:129], v[160:163], v[206:209], v[126:129]
	v_mfma_f32_16x16x32_bf16 v[122:125], v[168:171], v[206:209], v[122:125]
	v_mfma_f32_16x16x32_bf16 v[110:113], v[160:163], v[214:217], v[110:113]
	v_mfma_f32_16x16x32_bf16 v[106:109], v[168:171], v[214:217], v[106:109]
	v_mfma_f32_16x16x32_bf16 v[94:97], v[160:163], v[222:225], v[94:97]
	v_mfma_f32_16x16x32_bf16 v[90:93], v[168:171], v[222:225], v[90:93]
	v_mfma_f32_16x16x32_bf16 v[76:79], v[160:163], v[230:233], v[76:79]
	v_mfma_f32_16x16x32_bf16 v[72:75], v[168:171], v[230:233], v[72:75]
	v_mfma_f32_16x16x32_bf16 v[118:121], v[172:175], v[202:205], v[118:121]
	v_mfma_f32_16x16x32_bf16 v[114:117], v[180:183], v[202:205], v[114:117]
	v_mfma_f32_16x16x32_bf16 v[102:105], v[172:175], v[210:213], v[102:105]
	v_mfma_f32_16x16x32_bf16 v[98:101], v[180:183], v[210:213], v[98:101]
	v_mfma_f32_16x16x32_bf16 v[86:89], v[172:175], v[218:221], v[86:89]
	v_mfma_f32_16x16x32_bf16 v[82:85], v[180:183], v[218:221], v[82:85]
	v_mfma_f32_16x16x32_bf16 v[68:71], v[172:175], v[226:229], v[68:71]
	v_mfma_f32_16x16x32_bf16 v[64:67], v[180:183], v[226:229], v[64:67]
	v_mfma_f32_16x16x32_bf16 v[118:121], v[176:179], v[206:209], v[118:121]
	v_mfma_f32_16x16x32_bf16 v[114:117], v[184:187], v[206:209], v[114:117]
	v_mfma_f32_16x16x32_bf16 v[102:105], v[176:179], v[214:217], v[102:105]
	v_mfma_f32_16x16x32_bf16 v[98:101], v[184:187], v[214:217], v[98:101]
	v_mfma_f32_16x16x32_bf16 v[86:89], v[176:179], v[222:225], v[86:89]
	v_mfma_f32_16x16x32_bf16 v[82:85], v[184:187], v[222:225], v[82:85]
	v_mfma_f32_16x16x32_bf16 v[68:71], v[176:179], v[230:233], v[68:71]
	v_mfma_f32_16x16x32_bf16 v[64:67], v[184:187], v[230:233], v[64:67]
	s_barrier
; #define PG8_STAGE(bufoff, gbase, voff) do { _Pragma("unroll") for (int _i = 0; _i < 2; ++_i) \
;         __builtin_amdgcn_global_load_lds((const unsigned*)((const char*)(gbase) + (voff)[_i]), (PG8_LAS unsigned*)(lds + (bufoff) + ldsw + _i * 8192), 16, 0, 0); } while (0)
; #define PG8_LDA(dst, b, h) do { _Pragma("unroll") for (int m = 0; m < 4; ++m) _Pragma("unroll") for (int k = 0; k < 2; ++k) dst[m][k] = *(const PG8_LAS bf16x8*)(lds + PG8_SA(b, h) + aoff + m * 2048 + k * 1024); } while (0)
; #define PG8_MMA(ai, bj, At, Bt) do { __builtin_amdgcn_s_setprio(1); _Pragma("unroll") for (int m = 0; m < 4; ++m) _Pragma("unroll") for (int n = 0; n < 2; ++n) _Pragma("unroll") for (int k = 0; k < 2; ++k) \
;         acc[ai][bj][m][n] = __builtin_amdgcn_mfma_f32_16x16x32_bf16(Bt[n][k], At[m][k], acc[ai][bj][m][n], 0, 0, 0); __builtin_amdgcn_s_setprio(0); } while (0)
; #define PG8_WAIT_V(n) asm volatile("s_waitcnt vmcnt(" #n ")" ::: "memory")
; #define PG8_WAIT_L(n) asm volatile("s_waitcnt lgkmcnt(" #n ")" ::: "memory")
; #define PG8_BAR __builtin_amdgcn_s_barrier()
; #define PG8_SCHED __builtin_amdgcn_sched_barrier(0)
; template <class Epi, class Sched, bool ALIGN_EPI = false, bool SP2 = false, bool HALFM = false>
; __device__ __forceinline__ void gemm_phase(PG8_LAS unsigned char* lds, const Gemm g, const Sched& S, const Epi& E) {
;     ...
;         for (int t = 0; t < nt; t += 2) {
;     ...
;             if constexpr (!HALFM) PG8_LDA(At, 1, 1); PG8_STAGE(PG8_SB(1, 0), b3, voffB); PG8_STAGE(PG8_SB(1, 1), b3 + hstep, voffB); PG8_STAGE(PG8_SA(1, 0), a3, voffA);
;             PG8_WAIT_V(8); PG8_WAIT_L(0); PG8_BAR; if constexpr (!HALFM) { PG8_MMA(1, 0, At, B0); PG8_MMA(1, 1, At, B1); } PG8_BAR; PG8_SCHED;
	s_setprio 0
	s_add_i32 s26, s65, s46
	v_lshl_add_u64 v[140:141], v[140:141], 0, s[82:83]
	s_mov_b32 m0, s26
	ds_read_b128 v[202:205], v146 offset:49152
	ds_read_b128 v[206:209], v146 offset:50176
	ds_read_b128 v[210:213], v146 offset:51200
	ds_read_b128 v[214:217], v146 offset:52224
	ds_read_b128 v[218:221], v146 offset:53248
	ds_read_b128 v[222:225], v146 offset:54272
	ds_read_b128 v[226:229], v146 offset:55296
	ds_read_b128 v[230:233], v146 offset:56320
	global_load_lds_dwordx4 v[140:141], off
	s_add_i32 m0, s26, 0x2000
	s_add_u32 s24, s24, 0x40080
	v_lshl_add_u64 v[140:141], v[152:153], 0, s[82:83]
	s_addc_u32 s25, s25, 0
	s_add_i32 s26, s66, s46
	global_load_lds_dwordx4 v[140:141], off
	v_lshl_add_u64 v[140:141], s[24:25], 0, v[80:81]
	s_mov_b32 m0, s26
	s_nop 0
	global_load_lds_dwordx4 v[140:141], off
	v_lshl_add_u64 v[140:141], s[24:25], 0, v[134:135]
	s_add_i32 m0, s26, 0x2000
	s_nop 0
	global_load_lds_dwordx4 v[140:141], off
	v_lshl_add_u64 v[140:141], v[188:189], 0, s[82:83]
	s_mov_b32 m0, s51
	s_nop 0
	global_load_lds_dwordx4 v[140:141], off
	v_lshl_add_u64 v[140:141], v[196:197], 0, s[82:83]
	s_mov_b32 m0, s52
	s_nop 0
	global_load_lds_dwordx4 v[140:141], off
	s_waitcnt vmcnt(8)
	s_waitcnt lgkmcnt(0)
	s_setprio 1
	s_barrier
	v_mfma_f32_16x16x32_bf16 v[60:63], v[148:151], v[202:205], v[60:63]
	v_mfma_f32_16x16x32_bf16 v[56:59], v[164:167], v[202:205], v[56:59]
	v_mfma_f32_16x16x32_bf16 v[44:47], v[148:151], v[210:213], v[44:47]
	v_mfma_f32_16x16x32_bf16 v[40:43], v[164:167], v[210:213], v[40:43]
	v_mfma_f32_16x16x32_bf16 v[28:31], v[148:151], v[218:221], v[28:31]
	v_mfma_f32_16x16x32_bf16 v[24:27], v[164:167], v[218:221], v[24:27]
	v_mfma_f32_16x16x32_bf16 v[12:15], v[148:151], v[226:229], v[12:15]
	v_mfma_f32_16x16x32_bf16 v[8:11], v[164:167], v[226:229], v[8:11]
	v_mfma_f32_16x16x32_bf16 v[60:63], v[160:163], v[206:209], v[60:63]
	v_mfma_f32_16x16x32_bf16 v[56:59], v[168:171], v[206:209], v[56:59]
	v_mfma_f32_16x16x32_bf16 v[44:47], v[160:163], v[214:217], v[44:47]
	v_mfma_f32_16x16x32_bf16 v[40:43], v[168:171], v[214:217], v[40:43]
	v_mfma_f32_16x16x32_bf16 v[28:31], v[160:163], v[222:225], v[28:31]
	v_mfma_f32_16x16x32_bf16 v[24:27], v[168:171], v[222:225], v[24:27]
	v_mfma_f32_16x16x32_bf16 v[12:15], v[160:163], v[230:233], v[12:15]
	v_mfma_f32_16x16x32_bf16 v[8:11], v[168:171], v[230:233], v[8:11]
	v_mfma_f32_16x16x32_bf16 v[52:55], v[172:175], v[202:205], v[52:55]
	v_mfma_f32_16x16x32_bf16 v[48:51], v[180:183], v[202:205], v[48:51]
	v_mfma_f32_16x16x32_bf16 v[36:39], v[172:175], v[210:213], v[36:39]
	v_mfma_f32_16x16x32_bf16 v[32:35], v[180:183], v[210:213], v[32:35]
	v_mfma_f32_16x16x32_bf16 v[20:23], v[172:175], v[218:221], v[20:23]
	v_mfma_f32_16x16x32_bf16 v[16:19], v[180:183], v[218:221], v[16:19]
	v_mfma_f32_16x16x32_bf16 v[4:7], v[172:175], v[226:229], v[4:7]
	v_mfma_f32_16x16x32_bf16 v[0:3], v[180:183], v[226:229], v[0:3]
	v_mfma_f32_16x16x32_bf16 v[52:55], v[176:179], v[206:209], v[52:55]
	v_mfma_f32_16x16x32_bf16 v[48:51], v[184:187], v[206:209], v[48:51]
	v_mfma_f32_16x16x32_bf16 v[36:39], v[176:179], v[214:217], v[36:39]
	v_mfma_f32_16x16x32_bf16 v[32:35], v[184:187], v[214:217], v[32:35]
	v_mfma_f32_16x16x32_bf16 v[20:23], v[176:179], v[222:225], v[20:23]
	v_mfma_f32_16x16x32_bf16 v[16:19], v[184:187], v[222:225], v[16:19]
	v_mfma_f32_16x16x32_bf16 v[4:7], v[176:179], v[230:233], v[4:7]
	v_mfma_f32_16x16x32_bf16 v[0:3], v[184:187], v[230:233], v[0:3]
	s_barrier
	s_setprio 0
	s_add_i32 s64, s64, 2
	s_add_u32 s22, s22, 0x100
	s_addc_u32 s23, s23, 0
	s_add_u32 s62, s62, 0x100
	s_addc_u32 s63, s63, 0
	s_cmp_gt_u32 s64, 13
	s_cbranch_scc1 .LBB0_183
